# also: gate tile epilogue by hand (lnx g/b once per tile, dwordx4 Y/V loads and Y stores via v_permlane16_swap, next row group prefetched)
# speedup vs baseline: 1.0306x; 1.0122x over previous
.LBB0_1251:
	s_waitcnt lgkmcnt(0)
	v_lshl_or_b32 v156, s20, 7, v170
	v_add_u32_e32 v154, s19, v156
	s_lshl_b32 s0, s18, 6
	v_cmp_gt_i32_e32 vcc, s14, v154
	s_or_b32 s18, s0, s6
	v_mov_b64_e32 v[132:133], s[88:89]
	v_cndmask_b32_e32 v130, v168, v154, vcc
	v_mad_i64_i32 v[132:133], s[0:1], v130, s15, v[132:133]
	s_lshl_b32 s6, s18, 1
	s_waitcnt vmcnt(0)
	v_lshl_add_u64 v[132:133], v[132:133], 0, s[6:7]
	v_lshlrev_b32_e32 v0, 3, v169
	s_waitcnt lgkmcnt(0)
	s_barrier
	v_readlane_b32 s36, v192, 0
	v_readlane_b32 s37, v192, 1
	v_lshlrev_b32_e32 v0, 2, v169
	v_or_b32_e32 v0, s18, v0
	v_lshlrev_b32_e32 v254, 1, v0
	v_and_b32_e32 v250, 1, v169
	v_mul_u32_u24_e32 v250, 24, v250
	v_add_u32_e32 v254, v254, v250
	v_lshlrev_b32_e32 v0, 2, v0
	global_load_dwordx4 v[194:197], v0, s[26:27] offset:0
	global_load_dwordx4 v[198:201], v0, s[26:27] offset:64
	global_load_dwordx4 v[202:205], v0, s[26:27] offset:128
	global_load_dwordx4 v[206:209], v0, s[26:27] offset:192
	global_load_dwordx4 v[210:213], v0, s[36:37] offset:0
	global_load_dwordx4 v[214:217], v0, s[36:37] offset:64
	global_load_dwordx4 v[218:221], v0, s[36:37] offset:128
	global_load_dwordx4 v[222:225], v0, s[36:37] offset:192
	v_xor_b32_e32 v255, 16, v167
	v_lshlrev_b32_e32 v255, 2, v255
	v_xor_b32_e32 v193, 32, v167
	v_lshlrev_b32_e32 v193, 2, v193
	v_mov_b32_e32 v0, v156
	s_lshr_b32 s20, s18, 4
	s_mov_b32 s21, 0
	s_add_i32 s0, s19, 0
	v_add_u32_e32 v253, s0, v0
	v_cmp_gt_i32_e32 vcc, s14, v253
	s_nop 1
	v_cndmask_b32_e32 v253, v168, v253, vcc
	v_mov_b64_e32 v[148:149], s[88:89]
	v_mad_i64_i32 v[148:149], s[0:1], v253, s15, v[148:149]
	v_mov_b32_e32 v244, v254
	v_mov_b32_e32 v245, 0
	v_lshl_add_u64 v[148:149], v[148:149], 0, v[244:245]
	global_load_dwordx4 v[130:133], v[148:149], off offset:0
	global_load_dwordx4 v[134:137], v[148:149], off offset:64
	v_ashrrev_i32_e32 v251, 31, v253
	v_mov_b32_e32 v250, v253
	v_lshlrev_b64 v[246:247], 11, v[250:251]
	v_lshl_add_u64 v[246:247], s[54:55], 0, v[246:247]
	v_lshl_add_u64 v[246:247], v[246:247], 0, v[244:245]
	global_load_dwordx4 v[138:141], v[246:247], off offset:0
	global_load_dwordx4 v[142:145], v[246:247], off offset:64
	v_lshlrev_b64 v[246:247], 6, v[250:251]
	v_lshl_add_u64 v[246:247], s[58:59], 0, v[246:247]
	v_lshl_add_u64 v[246:247], v[246:247], 0, s[20:21]
	global_load_dword v146, v[246:247], off
	s_add_i32 s0, s19, 16
	v_add_u32_e32 v253, s0, v0
	v_cmp_gt_i32_e32 vcc, s14, v253
	s_nop 1
	v_cndmask_b32_e32 v253, v168, v253, vcc
	v_mov_b64_e32 v[226:227], s[88:89]
	v_mad_i64_i32 v[226:227], s[0:1], v253, s15, v[226:227]
	v_mov_b32_e32 v244, v254
	v_mov_b32_e32 v245, 0
	v_lshl_add_u64 v[226:227], v[226:227], 0, v[244:245]
	global_load_dwordx4 v[150:153], v[226:227], off offset:0
	global_load_dwordx4 v[154:157], v[226:227], off offset:64
	v_ashrrev_i32_e32 v251, 31, v253
	v_mov_b32_e32 v250, v253
	v_lshlrev_b64 v[246:247], 11, v[250:251]
	v_lshl_add_u64 v[246:247], s[54:55], 0, v[246:247]
	v_lshl_add_u64 v[246:247], v[246:247], 0, v[244:245]
	global_load_dwordx4 v[158:161], v[246:247], off offset:0
	global_load_dwordx4 v[162:165], v[246:247], off offset:64
	v_lshlrev_b64 v[246:247], 6, v[250:251]
	v_lshl_add_u64 v[246:247], s[58:59], 0, v[246:247]
	v_lshl_add_u64 v[246:247], v[246:247], 0, s[20:21]
	global_load_dword v147, v[246:247], off
	s_waitcnt vmcnt(5)
	v_permlane16_swap_b32_e32 v130, v132
	v_permlane16_swap_b32_e32 v131, v133
	v_permlane16_swap_b32_e32 v134, v136
	v_permlane16_swap_b32_e32 v135, v137
	v_permlane16_swap_b32_e32 v138, v140
	v_permlane16_swap_b32_e32 v139, v141
	v_permlane16_swap_b32_e32 v142, v144
	v_permlane16_swap_b32_e32 v143, v145
	v_lshlrev_b32_e32 v228, 16, v130
	v_and_b32_e32 v229, 0xffff0000, v130
	v_lshlrev_b32_e32 v230, 16, v131
	v_and_b32_e32 v231, 0xffff0000, v131
	v_lshlrev_b32_e32 v232, 16, v132
	v_and_b32_e32 v233, 0xffff0000, v132
	v_lshlrev_b32_e32 v234, 16, v133
	v_and_b32_e32 v235, 0xffff0000, v133
	v_lshlrev_b32_e32 v236, 16, v134
	v_and_b32_e32 v237, 0xffff0000, v134
	v_lshlrev_b32_e32 v238, 16, v135
	v_and_b32_e32 v239, 0xffff0000, v135
	v_lshlrev_b32_e32 v240, 16, v136
	v_and_b32_e32 v241, 0xffff0000, v136
	v_lshlrev_b32_e32 v242, 16, v137
	v_and_b32_e32 v243, 0xffff0000, v137
	v_add_f32_e32 v250, v228, v229
	v_add_f32_e32 v251, v230, v231
	v_add_f32_e32 v250, v250, v232
	v_add_f32_e32 v251, v251, v233
	v_add_f32_e32 v250, v250, v234
	v_add_f32_e32 v251, v251, v235
	v_add_f32_e32 v250, v250, v236
	v_add_f32_e32 v251, v251, v237
	v_add_f32_e32 v250, v250, v238
	v_add_f32_e32 v251, v251, v239
	v_add_f32_e32 v250, v250, v240
	v_add_f32_e32 v251, v251, v241
	v_add_f32_e32 v250, v250, v242
	v_add_f32_e32 v251, v251, v243
	v_add_f32_e32 v250, v250, v251
	ds_bpermute_b32 v251, v255, v250
	s_waitcnt lgkmcnt(0)
	v_add_f32_e32 v250, v250, v251
	ds_bpermute_b32 v251, v193, v250
	s_waitcnt lgkmcnt(0)
	v_add_f32_e32 v250, v250, v251
	v_fmac_f32_e32 v228, 0xbc800000, v250
	v_fmac_f32_e32 v229, 0xbc800000, v250
	v_fmac_f32_e32 v230, 0xbc800000, v250
	v_fmac_f32_e32 v231, 0xbc800000, v250
	v_fmac_f32_e32 v232, 0xbc800000, v250
	v_fmac_f32_e32 v233, 0xbc800000, v250
	v_fmac_f32_e32 v234, 0xbc800000, v250
	v_fmac_f32_e32 v235, 0xbc800000, v250
	v_fmac_f32_e32 v236, 0xbc800000, v250
	v_fmac_f32_e32 v237, 0xbc800000, v250
	v_fmac_f32_e32 v238, 0xbc800000, v250
	v_fmac_f32_e32 v239, 0xbc800000, v250
	v_fmac_f32_e32 v240, 0xbc800000, v250
	v_fmac_f32_e32 v241, 0xbc800000, v250
	v_fmac_f32_e32 v242, 0xbc800000, v250
	v_fmac_f32_e32 v243, 0xbc800000, v250
	v_mul_f32_e32 v250, v228, v228
	v_mul_f32_e32 v251, v229, v229
	v_fmac_f32_e32 v250, v230, v230
	v_fmac_f32_e32 v251, v231, v231
	v_fmac_f32_e32 v250, v232, v232
	v_fmac_f32_e32 v251, v233, v233
	v_fmac_f32_e32 v250, v234, v234
	v_fmac_f32_e32 v251, v235, v235
	v_fmac_f32_e32 v250, v236, v236
	v_fmac_f32_e32 v251, v237, v237
	v_fmac_f32_e32 v250, v238, v238
	v_fmac_f32_e32 v251, v239, v239
	v_fmac_f32_e32 v250, v240, v240
	v_fmac_f32_e32 v251, v241, v241
	v_fmac_f32_e32 v250, v242, v242
	v_fmac_f32_e32 v251, v243, v243
	v_add_f32_e32 v250, v250, v251
	ds_bpermute_b32 v251, v255, v250
	s_waitcnt lgkmcnt(0)
	v_add_f32_e32 v250, v250, v251
	ds_bpermute_b32 v251, v193, v250
	s_waitcnt lgkmcnt(0)
	v_add_f32_e32 v250, v250, v251
	v_fmamk_f32 v250, v250, 0x3c800000, v166
	v_mul_f32_e32 v251, 0x4b800000, v250
	v_cmp_gt_f32_e64 s[0:1], s16, v250
	s_nop 1
	v_cndmask_b32_e64 v250, v250, v251, s[0:1]
	v_rsq_f32_e32 v252, v250
	s_nop 0
	v_mul_f32_e32 v251, 0x45800000, v252
	v_cndmask_b32_e64 v252, v252, v251, s[0:1]
	v_mul_f32_e32 v228, v228, v252
	v_fma_f32 v228, v228, v194, v210
	v_lshlrev_b32_e32 v244, 16, v138
	v_fmac_f32_e32 v228, v146, v244
	v_mul_f32_e32 v228, v126, v228
	v_mul_f32_e32 v229, v229, v252
	v_fma_f32 v229, v229, v195, v211
	v_and_b32_e32 v244, 0xffff0000, v138
	v_fmac_f32_e32 v229, v146, v244
	v_mul_f32_e32 v229, v127, v229
	v_mul_f32_e32 v230, v230, v252
	v_fma_f32 v230, v230, v196, v212
	v_lshlrev_b32_e32 v244, 16, v139
	v_fmac_f32_e32 v230, v146, v244
	v_mul_f32_e32 v230, v128, v230
	v_mul_f32_e32 v231, v231, v252
	v_fma_f32 v231, v231, v197, v213
	v_and_b32_e32 v244, 0xffff0000, v139
	v_fmac_f32_e32 v231, v146, v244
	v_mul_f32_e32 v231, v129, v231
	v_mul_f32_e32 v232, v232, v252
	v_fma_f32 v232, v232, v198, v214
	v_lshlrev_b32_e32 v244, 16, v140
	v_fmac_f32_e32 v232, v146, v244
	v_mul_f32_e32 v232, v122, v232
	v_mul_f32_e32 v233, v233, v252
	v_fma_f32 v233, v233, v199, v215
	v_and_b32_e32 v244, 0xffff0000, v140
	v_fmac_f32_e32 v233, v146, v244
	v_mul_f32_e32 v233, v123, v233
	v_mul_f32_e32 v234, v234, v252
	v_fma_f32 v234, v234, v200, v216
	v_lshlrev_b32_e32 v244, 16, v141
	v_fmac_f32_e32 v234, v146, v244
	v_mul_f32_e32 v234, v124, v234
	v_mul_f32_e32 v235, v235, v252
	v_fma_f32 v235, v235, v201, v217
	v_and_b32_e32 v244, 0xffff0000, v141
	v_fmac_f32_e32 v235, v146, v244
	v_mul_f32_e32 v235, v125, v235
	v_mul_f32_e32 v236, v236, v252
	v_fma_f32 v236, v236, v202, v218
	v_lshlrev_b32_e32 v244, 16, v142
	v_fmac_f32_e32 v236, v146, v244
	v_mul_f32_e32 v236, v118, v236
	v_mul_f32_e32 v237, v237, v252
	v_fma_f32 v237, v237, v203, v219
	v_and_b32_e32 v244, 0xffff0000, v142
	v_fmac_f32_e32 v237, v146, v244
	v_mul_f32_e32 v237, v119, v237
	v_mul_f32_e32 v238, v238, v252
	v_fma_f32 v238, v238, v204, v220
	v_lshlrev_b32_e32 v244, 16, v143
	v_fmac_f32_e32 v238, v146, v244
	v_mul_f32_e32 v238, v120, v238
	v_mul_f32_e32 v239, v239, v252
	v_fma_f32 v239, v239, v205, v221
	v_and_b32_e32 v244, 0xffff0000, v143
	v_fmac_f32_e32 v239, v146, v244
	v_mul_f32_e32 v239, v121, v239
	v_mul_f32_e32 v240, v240, v252
	v_fma_f32 v240, v240, v206, v222
	v_lshlrev_b32_e32 v244, 16, v144
	v_fmac_f32_e32 v240, v146, v244
	v_mul_f32_e32 v240, v114, v240
	v_mul_f32_e32 v241, v241, v252
	v_fma_f32 v241, v241, v207, v223
	v_and_b32_e32 v244, 0xffff0000, v144
	v_fmac_f32_e32 v241, v146, v244
	v_mul_f32_e32 v241, v115, v241
	v_mul_f32_e32 v242, v242, v252
	v_fma_f32 v242, v242, v208, v224
	v_lshlrev_b32_e32 v244, 16, v145
	v_fmac_f32_e32 v242, v146, v244
	v_mul_f32_e32 v242, v116, v242
	v_mul_f32_e32 v243, v243, v252
	v_fma_f32 v243, v243, v209, v225
	v_and_b32_e32 v244, 0xffff0000, v145
	v_fmac_f32_e32 v243, v146, v244
	v_mul_f32_e32 v243, v117, v243
	v_cvt_pk_bf16_f32 v228, v228, v229
	v_cvt_pk_bf16_f32 v229, v230, v231
	v_cvt_pk_bf16_f32 v230, v232, v233
	v_cvt_pk_bf16_f32 v231, v234, v235
	v_cvt_pk_bf16_f32 v232, v236, v237
	v_cvt_pk_bf16_f32 v233, v238, v239
	v_cvt_pk_bf16_f32 v234, v240, v241
	v_cvt_pk_bf16_f32 v235, v242, v243
	s_nop 1
	v_permlane16_swap_b32_e32 v228, v230
	v_permlane16_swap_b32_e32 v229, v231
	v_permlane16_swap_b32_e32 v232, v234
	v_permlane16_swap_b32_e32 v233, v235
	v_mov_b64_e32 v[248:249], v[148:149]
	s_add_i32 s0, s19, 32
	v_add_u32_e32 v253, s0, v0
	v_cmp_gt_i32_e32 vcc, s14, v253
	s_nop 1
	v_cndmask_b32_e32 v253, v168, v253, vcc
	v_mov_b64_e32 v[148:149], s[88:89]
	v_mad_i64_i32 v[148:149], s[0:1], v253, s15, v[148:149]
	v_mov_b32_e32 v244, v254
	v_mov_b32_e32 v245, 0
	v_lshl_add_u64 v[148:149], v[148:149], 0, v[244:245]
	global_load_dwordx4 v[130:133], v[148:149], off offset:0
	global_load_dwordx4 v[134:137], v[148:149], off offset:64
	v_ashrrev_i32_e32 v251, 31, v253
	v_mov_b32_e32 v250, v253
	v_lshlrev_b64 v[246:247], 11, v[250:251]
	v_lshl_add_u64 v[246:247], s[54:55], 0, v[246:247]
	v_lshl_add_u64 v[246:247], v[246:247], 0, v[244:245]
	global_load_dwordx4 v[138:141], v[246:247], off offset:0
	global_load_dwordx4 v[142:145], v[246:247], off offset:64
	v_lshlrev_b64 v[246:247], 6, v[250:251]
	v_lshl_add_u64 v[246:247], s[58:59], 0, v[246:247]
	v_lshl_add_u64 v[246:247], v[246:247], 0, s[20:21]
	global_load_dword v146, v[246:247], off
	s_add_i32 s0, s19, 0
	v_add_u32_e32 v253, s0, v0
	v_cmp_gt_i32_e32 vcc, s14, v253
	s_and_saveexec_b64 s[0:1], vcc
	global_store_dwordx4 v[248:249], v[228:231], off offset:0
	global_store_dwordx4 v[248:249], v[232:235], off offset:64
	s_or_b64 exec, exec, s[0:1]
	s_waitcnt vmcnt(5)
	v_permlane16_swap_b32_e32 v150, v152
	v_permlane16_swap_b32_e32 v151, v153
	v_permlane16_swap_b32_e32 v154, v156
	v_permlane16_swap_b32_e32 v155, v157
	v_permlane16_swap_b32_e32 v158, v160
	v_permlane16_swap_b32_e32 v159, v161
	v_permlane16_swap_b32_e32 v162, v164
	v_permlane16_swap_b32_e32 v163, v165
	v_lshlrev_b32_e32 v228, 16, v150
	v_and_b32_e32 v229, 0xffff0000, v150
	v_lshlrev_b32_e32 v230, 16, v151
	v_and_b32_e32 v231, 0xffff0000, v151
	v_lshlrev_b32_e32 v232, 16, v152
	v_and_b32_e32 v233, 0xffff0000, v152
	v_lshlrev_b32_e32 v234, 16, v153
	v_and_b32_e32 v235, 0xffff0000, v153
	v_lshlrev_b32_e32 v236, 16, v154
	v_and_b32_e32 v237, 0xffff0000, v154
	v_lshlrev_b32_e32 v238, 16, v155
	v_and_b32_e32 v239, 0xffff0000, v155
	v_lshlrev_b32_e32 v240, 16, v156
	v_and_b32_e32 v241, 0xffff0000, v156
	v_lshlrev_b32_e32 v242, 16, v157
	v_and_b32_e32 v243, 0xffff0000, v157
	v_add_f32_e32 v250, v228, v229
	v_add_f32_e32 v251, v230, v231
	v_add_f32_e32 v250, v250, v232
	v_add_f32_e32 v251, v251, v233
	v_add_f32_e32 v250, v250, v234
	v_add_f32_e32 v251, v251, v235
	v_add_f32_e32 v250, v250, v236
	v_add_f32_e32 v251, v251, v237
	v_add_f32_e32 v250, v250, v238
	v_add_f32_e32 v251, v251, v239
	v_add_f32_e32 v250, v250, v240
	v_add_f32_e32 v251, v251, v241
	v_add_f32_e32 v250, v250, v242
	v_add_f32_e32 v251, v251, v243
	v_add_f32_e32 v250, v250, v251
	ds_bpermute_b32 v251, v255, v250
	s_waitcnt lgkmcnt(0)
	v_add_f32_e32 v250, v250, v251
	ds_bpermute_b32 v251, v193, v250
	s_waitcnt lgkmcnt(0)
	v_add_f32_e32 v250, v250, v251
	v_fmac_f32_e32 v228, 0xbc800000, v250
	v_fmac_f32_e32 v229, 0xbc800000, v250
	v_fmac_f32_e32 v230, 0xbc800000, v250
	v_fmac_f32_e32 v231, 0xbc800000, v250
	v_fmac_f32_e32 v232, 0xbc800000, v250
	v_fmac_f32_e32 v233, 0xbc800000, v250
	v_fmac_f32_e32 v234, 0xbc800000, v250
	v_fmac_f32_e32 v235, 0xbc800000, v250
	v_fmac_f32_e32 v236, 0xbc800000, v250
	v_fmac_f32_e32 v237, 0xbc800000, v250
	v_fmac_f32_e32 v238, 0xbc800000, v250
	v_fmac_f32_e32 v239, 0xbc800000, v250
	v_fmac_f32_e32 v240, 0xbc800000, v250
	v_fmac_f32_e32 v241, 0xbc800000, v250
	v_fmac_f32_e32 v242, 0xbc800000, v250
	v_fmac_f32_e32 v243, 0xbc800000, v250
	v_mul_f32_e32 v250, v228, v228
	v_mul_f32_e32 v251, v229, v229
	v_fmac_f32_e32 v250, v230, v230
	v_fmac_f32_e32 v251, v231, v231
	v_fmac_f32_e32 v250, v232, v232
	v_fmac_f32_e32 v251, v233, v233
	v_fmac_f32_e32 v250, v234, v234
	v_fmac_f32_e32 v251, v235, v235
	v_fmac_f32_e32 v250, v236, v236
	v_fmac_f32_e32 v251, v237, v237
	v_fmac_f32_e32 v250, v238, v238
	v_fmac_f32_e32 v251, v239, v239
	v_fmac_f32_e32 v250, v240, v240
	v_fmac_f32_e32 v251, v241, v241
	v_fmac_f32_e32 v250, v242, v242
	v_fmac_f32_e32 v251, v243, v243
	v_add_f32_e32 v250, v250, v251
	ds_bpermute_b32 v251, v255, v250
	s_waitcnt lgkmcnt(0)
	v_add_f32_e32 v250, v250, v251
	ds_bpermute_b32 v251, v193, v250
	s_waitcnt lgkmcnt(0)
	v_add_f32_e32 v250, v250, v251
	v_fmamk_f32 v250, v250, 0x3c800000, v166
	v_mul_f32_e32 v251, 0x4b800000, v250
	v_cmp_gt_f32_e64 s[0:1], s16, v250
	s_nop 1
	v_cndmask_b32_e64 v250, v250, v251, s[0:1]
	v_rsq_f32_e32 v252, v250
	s_nop 0
	v_mul_f32_e32 v251, 0x45800000, v252
	v_cndmask_b32_e64 v252, v252, v251, s[0:1]
	v_mul_f32_e32 v228, v228, v252
	v_fma_f32 v228, v228, v194, v210
	v_lshlrev_b32_e32 v244, 16, v158
	v_fmac_f32_e32 v228, v147, v244
	v_mul_f32_e32 v228, v110, v228
	v_mul_f32_e32 v229, v229, v252
	v_fma_f32 v229, v229, v195, v211
	v_and_b32_e32 v244, 0xffff0000, v158
	v_fmac_f32_e32 v229, v147, v244
	v_mul_f32_e32 v229, v111, v229
	v_mul_f32_e32 v230, v230, v252
	v_fma_f32 v230, v230, v196, v212
	v_lshlrev_b32_e32 v244, 16, v159
	v_fmac_f32_e32 v230, v147, v244
	v_mul_f32_e32 v230, v112, v230
	v_mul_f32_e32 v231, v231, v252
	v_fma_f32 v231, v231, v197, v213
	v_and_b32_e32 v244, 0xffff0000, v159
	v_fmac_f32_e32 v231, v147, v244
	v_mul_f32_e32 v231, v113, v231
	v_mul_f32_e32 v232, v232, v252
	v_fma_f32 v232, v232, v198, v214
	v_lshlrev_b32_e32 v244, 16, v160
	v_fmac_f32_e32 v232, v147, v244
	v_mul_f32_e32 v232, v106, v232
	v_mul_f32_e32 v233, v233, v252
	v_fma_f32 v233, v233, v199, v215
	v_and_b32_e32 v244, 0xffff0000, v160
	v_fmac_f32_e32 v233, v147, v244
	v_mul_f32_e32 v233, v107, v233
	v_mul_f32_e32 v234, v234, v252
	v_fma_f32 v234, v234, v200, v216
	v_lshlrev_b32_e32 v244, 16, v161
	v_fmac_f32_e32 v234, v147, v244
	v_mul_f32_e32 v234, v108, v234
	v_mul_f32_e32 v235, v235, v252
	v_fma_f32 v235, v235, v201, v217
	v_and_b32_e32 v244, 0xffff0000, v161
	v_fmac_f32_e32 v235, v147, v244
	v_mul_f32_e32 v235, v109, v235
	v_mul_f32_e32 v236, v236, v252
	v_fma_f32 v236, v236, v202, v218
	v_lshlrev_b32_e32 v244, 16, v162
	v_fmac_f32_e32 v236, v147, v244
	v_mul_f32_e32 v236, v102, v236
	v_mul_f32_e32 v237, v237, v252
	v_fma_f32 v237, v237, v203, v219
	v_and_b32_e32 v244, 0xffff0000, v162
	v_fmac_f32_e32 v237, v147, v244
	v_mul_f32_e32 v237, v103, v237
	v_mul_f32_e32 v238, v238, v252
	v_fma_f32 v238, v238, v204, v220
	v_lshlrev_b32_e32 v244, 16, v163
	v_fmac_f32_e32 v238, v147, v244
	v_mul_f32_e32 v238, v104, v238
	v_mul_f32_e32 v239, v239, v252
	v_fma_f32 v239, v239, v205, v221
	v_and_b32_e32 v244, 0xffff0000, v163
	v_fmac_f32_e32 v239, v147, v244
	v_mul_f32_e32 v239, v105, v239
	v_mul_f32_e32 v240, v240, v252
	v_fma_f32 v240, v240, v206, v222
	v_lshlrev_b32_e32 v244, 16, v164
	v_fmac_f32_e32 v240, v147, v244
	v_mul_f32_e32 v240, v98, v240
	v_mul_f32_e32 v241, v241, v252
	v_fma_f32 v241, v241, v207, v223
	v_and_b32_e32 v244, 0xffff0000, v164
	v_fmac_f32_e32 v241, v147, v244
	v_mul_f32_e32 v241, v99, v241
	v_mul_f32_e32 v242, v242, v252
	v_fma_f32 v242, v242, v208, v224
	v_lshlrev_b32_e32 v244, 16, v165
	v_fmac_f32_e32 v242, v147, v244
	v_mul_f32_e32 v242, v100, v242
	v_mul_f32_e32 v243, v243, v252
	v_fma_f32 v243, v243, v209, v225
	v_and_b32_e32 v244, 0xffff0000, v165
	v_fmac_f32_e32 v243, v147, v244
	v_mul_f32_e32 v243, v101, v243
	v_cvt_pk_bf16_f32 v228, v228, v229
	v_cvt_pk_bf16_f32 v229, v230, v231
	v_cvt_pk_bf16_f32 v230, v232, v233
	v_cvt_pk_bf16_f32 v231, v234, v235
	v_cvt_pk_bf16_f32 v232, v236, v237
	v_cvt_pk_bf16_f32 v233, v238, v239
	v_cvt_pk_bf16_f32 v234, v240, v241
	v_cvt_pk_bf16_f32 v235, v242, v243
	s_nop 1
	v_permlane16_swap_b32_e32 v228, v230
	v_permlane16_swap_b32_e32 v229, v231
	v_permlane16_swap_b32_e32 v232, v234
	v_permlane16_swap_b32_e32 v233, v235
	v_mov_b64_e32 v[248:249], v[226:227]
	s_add_i32 s0, s19, 48
	v_add_u32_e32 v253, s0, v0
	v_cmp_gt_i32_e32 vcc, s14, v253
	s_nop 1
	v_cndmask_b32_e32 v253, v168, v253, vcc
	v_mov_b64_e32 v[226:227], s[88:89]
	v_mad_i64_i32 v[226:227], s[0:1], v253, s15, v[226:227]
	v_mov_b32_e32 v244, v254
	v_mov_b32_e32 v245, 0
	v_lshl_add_u64 v[226:227], v[226:227], 0, v[244:245]
	global_load_dwordx4 v[150:153], v[226:227], off offset:0
	global_load_dwordx4 v[154:157], v[226:227], off offset:64
	v_ashrrev_i32_e32 v251, 31, v253
	v_mov_b32_e32 v250, v253
	v_lshlrev_b64 v[246:247], 11, v[250:251]
	v_lshl_add_u64 v[246:247], s[54:55], 0, v[246:247]
	v_lshl_add_u64 v[246:247], v[246:247], 0, v[244:245]
	global_load_dwordx4 v[158:161], v[246:247], off offset:0
	global_load_dwordx4 v[162:165], v[246:247], off offset:64
	v_lshlrev_b64 v[246:247], 6, v[250:251]
	v_lshl_add_u64 v[246:247], s[58:59], 0, v[246:247]
	v_lshl_add_u64 v[246:247], v[246:247], 0, s[20:21]
	global_load_dword v147, v[246:247], off
	s_add_i32 s0, s19, 16
	v_add_u32_e32 v253, s0, v0
	v_cmp_gt_i32_e32 vcc, s14, v253
	s_and_saveexec_b64 s[0:1], vcc
	global_store_dwordx4 v[248:249], v[228:231], off offset:0
	global_store_dwordx4 v[248:249], v[232:235], off offset:64
	s_or_b64 exec, exec, s[0:1]
	s_waitcnt vmcnt(5)
	v_permlane16_swap_b32_e32 v130, v132
	v_permlane16_swap_b32_e32 v131, v133
	v_permlane16_swap_b32_e32 v134, v136
	v_permlane16_swap_b32_e32 v135, v137
	v_permlane16_swap_b32_e32 v138, v140
	v_permlane16_swap_b32_e32 v139, v141
	v_permlane16_swap_b32_e32 v142, v144
	v_permlane16_swap_b32_e32 v143, v145
	v_lshlrev_b32_e32 v228, 16, v130
	v_and_b32_e32 v229, 0xffff0000, v130
	v_lshlrev_b32_e32 v230, 16, v131
	v_and_b32_e32 v231, 0xffff0000, v131
	v_lshlrev_b32_e32 v232, 16, v132
	v_and_b32_e32 v233, 0xffff0000, v132
	v_lshlrev_b32_e32 v234, 16, v133
	v_and_b32_e32 v235, 0xffff0000, v133
	v_lshlrev_b32_e32 v236, 16, v134
	v_and_b32_e32 v237, 0xffff0000, v134
	v_lshlrev_b32_e32 v238, 16, v135
	v_and_b32_e32 v239, 0xffff0000, v135
	v_lshlrev_b32_e32 v240, 16, v136
	v_and_b32_e32 v241, 0xffff0000, v136
	v_lshlrev_b32_e32 v242, 16, v137
	v_and_b32_e32 v243, 0xffff0000, v137
	v_add_f32_e32 v250, v228, v229
	v_add_f32_e32 v251, v230, v231
	v_add_f32_e32 v250, v250, v232
	v_add_f32_e32 v251, v251, v233
	v_add_f32_e32 v250, v250, v234
	v_add_f32_e32 v251, v251, v235
	v_add_f32_e32 v250, v250, v236
	v_add_f32_e32 v251, v251, v237
	v_add_f32_e32 v250, v250, v238
	v_add_f32_e32 v251, v251, v239
	v_add_f32_e32 v250, v250, v240
	v_add_f32_e32 v251, v251, v241
	v_add_f32_e32 v250, v250, v242
	v_add_f32_e32 v251, v251, v243
	v_add_f32_e32 v250, v250, v251
	ds_bpermute_b32 v251, v255, v250
	s_waitcnt lgkmcnt(0)
	v_add_f32_e32 v250, v250, v251
	ds_bpermute_b32 v251, v193, v250
	s_waitcnt lgkmcnt(0)
	v_add_f32_e32 v250, v250, v251
	v_fmac_f32_e32 v228, 0xbc800000, v250
	v_fmac_f32_e32 v229, 0xbc800000, v250
	v_fmac_f32_e32 v230, 0xbc800000, v250
	v_fmac_f32_e32 v231, 0xbc800000, v250
	v_fmac_f32_e32 v232, 0xbc800000, v250
	v_fmac_f32_e32 v233, 0xbc800000, v250
	v_fmac_f32_e32 v234, 0xbc800000, v250
	v_fmac_f32_e32 v235, 0xbc800000, v250
	v_fmac_f32_e32 v236, 0xbc800000, v250
	v_fmac_f32_e32 v237, 0xbc800000, v250
	v_fmac_f32_e32 v238, 0xbc800000, v250
	v_fmac_f32_e32 v239, 0xbc800000, v250
	v_fmac_f32_e32 v240, 0xbc800000, v250
	v_fmac_f32_e32 v241, 0xbc800000, v250
	v_fmac_f32_e32 v242, 0xbc800000, v250
	v_fmac_f32_e32 v243, 0xbc800000, v250
	v_mul_f32_e32 v250, v228, v228
	v_mul_f32_e32 v251, v229, v229
	v_fmac_f32_e32 v250, v230, v230
	v_fmac_f32_e32 v251, v231, v231
	v_fmac_f32_e32 v250, v232, v232
	v_fmac_f32_e32 v251, v233, v233
	v_fmac_f32_e32 v250, v234, v234
	v_fmac_f32_e32 v251, v235, v235
	v_fmac_f32_e32 v250, v236, v236
	v_fmac_f32_e32 v251, v237, v237
	v_fmac_f32_e32 v250, v238, v238
	v_fmac_f32_e32 v251, v239, v239
	v_fmac_f32_e32 v250, v240, v240
	v_fmac_f32_e32 v251, v241, v241
	v_fmac_f32_e32 v250, v242, v242
	v_fmac_f32_e32 v251, v243, v243
	v_add_f32_e32 v250, v250, v251
	ds_bpermute_b32 v251, v255, v250
	s_waitcnt lgkmcnt(0)
	v_add_f32_e32 v250, v250, v251
	ds_bpermute_b32 v251, v193, v250
	s_waitcnt lgkmcnt(0)
	v_add_f32_e32 v250, v250, v251
	v_fmamk_f32 v250, v250, 0x3c800000, v166
	v_mul_f32_e32 v251, 0x4b800000, v250
	v_cmp_gt_f32_e64 s[0:1], s16, v250
	s_nop 1
	v_cndmask_b32_e64 v250, v250, v251, s[0:1]
	v_rsq_f32_e32 v252, v250
	s_nop 0
	v_mul_f32_e32 v251, 0x45800000, v252
	v_cndmask_b32_e64 v252, v252, v251, s[0:1]
	v_mul_f32_e32 v228, v228, v252
	v_fma_f32 v228, v228, v194, v210
	v_lshlrev_b32_e32 v244, 16, v138
	v_fmac_f32_e32 v228, v146, v244
	v_mul_f32_e32 v228, v94, v228
	v_mul_f32_e32 v229, v229, v252
	v_fma_f32 v229, v229, v195, v211
	v_and_b32_e32 v244, 0xffff0000, v138
	v_fmac_f32_e32 v229, v146, v244
	v_mul_f32_e32 v229, v95, v229
	v_mul_f32_e32 v230, v230, v252
	v_fma_f32 v230, v230, v196, v212
	v_lshlrev_b32_e32 v244, 16, v139
	v_fmac_f32_e32 v230, v146, v244
	v_mul_f32_e32 v230, v96, v230
	v_mul_f32_e32 v231, v231, v252
	v_fma_f32 v231, v231, v197, v213
	v_and_b32_e32 v244, 0xffff0000, v139
	v_fmac_f32_e32 v231, v146, v244
	v_mul_f32_e32 v231, v97, v231
	v_mul_f32_e32 v232, v232, v252
	v_fma_f32 v232, v232, v198, v214
	v_lshlrev_b32_e32 v244, 16, v140
	v_fmac_f32_e32 v232, v146, v244
	v_mul_f32_e32 v232, v90, v232
	v_mul_f32_e32 v233, v233, v252
	v_fma_f32 v233, v233, v199, v215
	v_and_b32_e32 v244, 0xffff0000, v140
	v_fmac_f32_e32 v233, v146, v244
	v_mul_f32_e32 v233, v91, v233
	v_mul_f32_e32 v234, v234, v252
	v_fma_f32 v234, v234, v200, v216
	v_lshlrev_b32_e32 v244, 16, v141
	v_fmac_f32_e32 v234, v146, v244
	v_mul_f32_e32 v234, v92, v234
	v_mul_f32_e32 v235, v235, v252
	v_fma_f32 v235, v235, v201, v217
	v_and_b32_e32 v244, 0xffff0000, v141
	v_fmac_f32_e32 v235, v146, v244
	v_mul_f32_e32 v235, v93, v235
	v_mul_f32_e32 v236, v236, v252
	v_fma_f32 v236, v236, v202, v218
	v_lshlrev_b32_e32 v244, 16, v142
	v_fmac_f32_e32 v236, v146, v244
	v_mul_f32_e32 v236, v86, v236
	v_mul_f32_e32 v237, v237, v252
	v_fma_f32 v237, v237, v203, v219
	v_and_b32_e32 v244, 0xffff0000, v142
	v_fmac_f32_e32 v237, v146, v244
	v_mul_f32_e32 v237, v87, v237
	v_mul_f32_e32 v238, v238, v252
	v_fma_f32 v238, v238, v204, v220
	v_lshlrev_b32_e32 v244, 16, v143
	v_fmac_f32_e32 v238, v146, v244
	v_mul_f32_e32 v238, v88, v238
	v_mul_f32_e32 v239, v239, v252
	v_fma_f32 v239, v239, v205, v221
	v_and_b32_e32 v244, 0xffff0000, v143
	v_fmac_f32_e32 v239, v146, v244
	v_mul_f32_e32 v239, v89, v239
	v_mul_f32_e32 v240, v240, v252
	v_fma_f32 v240, v240, v206, v222
	v_lshlrev_b32_e32 v244, 16, v144
	v_fmac_f32_e32 v240, v146, v244
	v_mul_f32_e32 v240, v82, v240
	v_mul_f32_e32 v241, v241, v252
	v_fma_f32 v241, v241, v207, v223
	v_and_b32_e32 v244, 0xffff0000, v144
	v_fmac_f32_e32 v241, v146, v244
	v_mul_f32_e32 v241, v83, v241
	v_mul_f32_e32 v242, v242, v252
	v_fma_f32 v242, v242, v208, v224
	v_lshlrev_b32_e32 v244, 16, v145
	v_fmac_f32_e32 v242, v146, v244
	v_mul_f32_e32 v242, v84, v242
	v_mul_f32_e32 v243, v243, v252
	v_fma_f32 v243, v243, v209, v225
	v_and_b32_e32 v244, 0xffff0000, v145
	v_fmac_f32_e32 v243, v146, v244
	v_mul_f32_e32 v243, v85, v243
	v_cvt_pk_bf16_f32 v228, v228, v229
	v_cvt_pk_bf16_f32 v229, v230, v231
	v_cvt_pk_bf16_f32 v230, v232, v233
	v_cvt_pk_bf16_f32 v231, v234, v235
	v_cvt_pk_bf16_f32 v232, v236, v237
	v_cvt_pk_bf16_f32 v233, v238, v239
	v_cvt_pk_bf16_f32 v234, v240, v241
	v_cvt_pk_bf16_f32 v235, v242, v243
	s_nop 1
	v_permlane16_swap_b32_e32 v228, v230
	v_permlane16_swap_b32_e32 v229, v231
	v_permlane16_swap_b32_e32 v232, v234
	v_permlane16_swap_b32_e32 v233, v235
	v_mov_b64_e32 v[248:249], v[148:149]
	s_add_i32 s0, s19, 64
	v_add_u32_e32 v253, s0, v0
	v_cmp_gt_i32_e32 vcc, s14, v253
	s_nop 1
	v_cndmask_b32_e32 v253, v168, v253, vcc
	v_mov_b64_e32 v[148:149], s[88:89]
	v_mad_i64_i32 v[148:149], s[0:1], v253, s15, v[148:149]
	v_mov_b32_e32 v244, v254
	v_mov_b32_e32 v245, 0
	v_lshl_add_u64 v[148:149], v[148:149], 0, v[244:245]
	global_load_dwordx4 v[130:133], v[148:149], off offset:0
	global_load_dwordx4 v[134:137], v[148:149], off offset:64
	v_ashrrev_i32_e32 v251, 31, v253
	v_mov_b32_e32 v250, v253
	v_lshlrev_b64 v[246:247], 11, v[250:251]
	v_lshl_add_u64 v[246:247], s[54:55], 0, v[246:247]
	v_lshl_add_u64 v[246:247], v[246:247], 0, v[244:245]
	global_load_dwordx4 v[138:141], v[246:247], off offset:0
	global_load_dwordx4 v[142:145], v[246:247], off offset:64
	v_lshlrev_b64 v[246:247], 6, v[250:251]
	v_lshl_add_u64 v[246:247], s[58:59], 0, v[246:247]
	v_lshl_add_u64 v[246:247], v[246:247], 0, s[20:21]
	global_load_dword v146, v[246:247], off
	s_add_i32 s0, s19, 32
	v_add_u32_e32 v253, s0, v0
	v_cmp_gt_i32_e32 vcc, s14, v253
	s_and_saveexec_b64 s[0:1], vcc
	global_store_dwordx4 v[248:249], v[228:231], off offset:0
	global_store_dwordx4 v[248:249], v[232:235], off offset:64
	s_or_b64 exec, exec, s[0:1]
	s_waitcnt vmcnt(5)
	v_permlane16_swap_b32_e32 v150, v152
	v_permlane16_swap_b32_e32 v151, v153
	v_permlane16_swap_b32_e32 v154, v156
	v_permlane16_swap_b32_e32 v155, v157
	v_permlane16_swap_b32_e32 v158, v160
	v_permlane16_swap_b32_e32 v159, v161
	v_permlane16_swap_b32_e32 v162, v164
	v_permlane16_swap_b32_e32 v163, v165
	v_lshlrev_b32_e32 v228, 16, v150
	v_and_b32_e32 v229, 0xffff0000, v150
	v_lshlrev_b32_e32 v230, 16, v151
	v_and_b32_e32 v231, 0xffff0000, v151
	v_lshlrev_b32_e32 v232, 16, v152
	v_and_b32_e32 v233, 0xffff0000, v152
	v_lshlrev_b32_e32 v234, 16, v153
	v_and_b32_e32 v235, 0xffff0000, v153
	v_lshlrev_b32_e32 v236, 16, v154
	v_and_b32_e32 v237, 0xffff0000, v154
	v_lshlrev_b32_e32 v238, 16, v155
	v_and_b32_e32 v239, 0xffff0000, v155
	v_lshlrev_b32_e32 v240, 16, v156
	v_and_b32_e32 v241, 0xffff0000, v156
	v_lshlrev_b32_e32 v242, 16, v157
	v_and_b32_e32 v243, 0xffff0000, v157
	v_add_f32_e32 v250, v228, v229
	v_add_f32_e32 v251, v230, v231
	v_add_f32_e32 v250, v250, v232
	v_add_f32_e32 v251, v251, v233
	v_add_f32_e32 v250, v250, v234
	v_add_f32_e32 v251, v251, v235
	v_add_f32_e32 v250, v250, v236
	v_add_f32_e32 v251, v251, v237
	v_add_f32_e32 v250, v250, v238
	v_add_f32_e32 v251, v251, v239
	v_add_f32_e32 v250, v250, v240
	v_add_f32_e32 v251, v251, v241
	v_add_f32_e32 v250, v250, v242
	v_add_f32_e32 v251, v251, v243
	v_add_f32_e32 v250, v250, v251
	ds_bpermute_b32 v251, v255, v250
	s_waitcnt lgkmcnt(0)
	v_add_f32_e32 v250, v250, v251
	ds_bpermute_b32 v251, v193, v250
	s_waitcnt lgkmcnt(0)
	v_add_f32_e32 v250, v250, v251
	v_fmac_f32_e32 v228, 0xbc800000, v250
	v_fmac_f32_e32 v229, 0xbc800000, v250
	v_fmac_f32_e32 v230, 0xbc800000, v250
	v_fmac_f32_e32 v231, 0xbc800000, v250
	v_fmac_f32_e32 v232, 0xbc800000, v250
	v_fmac_f32_e32 v233, 0xbc800000, v250
	v_fmac_f32_e32 v234, 0xbc800000, v250
	v_fmac_f32_e32 v235, 0xbc800000, v250
	v_fmac_f32_e32 v236, 0xbc800000, v250
	v_fmac_f32_e32 v237, 0xbc800000, v250
	v_fmac_f32_e32 v238, 0xbc800000, v250
	v_fmac_f32_e32 v239, 0xbc800000, v250
	v_fmac_f32_e32 v240, 0xbc800000, v250
	v_fmac_f32_e32 v241, 0xbc800000, v250
	v_fmac_f32_e32 v242, 0xbc800000, v250
	v_fmac_f32_e32 v243, 0xbc800000, v250
	v_mul_f32_e32 v250, v228, v228
	v_mul_f32_e32 v251, v229, v229
	v_fmac_f32_e32 v250, v230, v230
	v_fmac_f32_e32 v251, v231, v231
	v_fmac_f32_e32 v250, v232, v232
	v_fmac_f32_e32 v251, v233, v233
	v_fmac_f32_e32 v250, v234, v234
	v_fmac_f32_e32 v251, v235, v235
	v_fmac_f32_e32 v250, v236, v236
	v_fmac_f32_e32 v251, v237, v237
	v_fmac_f32_e32 v250, v238, v238
	v_fmac_f32_e32 v251, v239, v239
	v_fmac_f32_e32 v250, v240, v240
	v_fmac_f32_e32 v251, v241, v241
	v_fmac_f32_e32 v250, v242, v242
	v_fmac_f32_e32 v251, v243, v243
	v_add_f32_e32 v250, v250, v251
	ds_bpermute_b32 v251, v255, v250
	s_waitcnt lgkmcnt(0)
	v_add_f32_e32 v250, v250, v251
	ds_bpermute_b32 v251, v193, v250
	s_waitcnt lgkmcnt(0)
	v_add_f32_e32 v250, v250, v251
	v_fmamk_f32 v250, v250, 0x3c800000, v166
	v_mul_f32_e32 v251, 0x4b800000, v250
	v_cmp_gt_f32_e64 s[0:1], s16, v250
	s_nop 1
	v_cndmask_b32_e64 v250, v250, v251, s[0:1]
	v_rsq_f32_e32 v252, v250
	s_nop 0
	v_mul_f32_e32 v251, 0x45800000, v252
	v_cndmask_b32_e64 v252, v252, v251, s[0:1]
	v_mul_f32_e32 v228, v228, v252
	v_fma_f32 v228, v228, v194, v210
	v_lshlrev_b32_e32 v244, 16, v158
	v_fmac_f32_e32 v228, v147, v244
	v_mul_f32_e32 v228, v78, v228
	v_mul_f32_e32 v229, v229, v252
	v_fma_f32 v229, v229, v195, v211
	v_and_b32_e32 v244, 0xffff0000, v158
	v_fmac_f32_e32 v229, v147, v244
	v_mul_f32_e32 v229, v79, v229
	v_mul_f32_e32 v230, v230, v252
	v_fma_f32 v230, v230, v196, v212
	v_lshlrev_b32_e32 v244, 16, v159
	v_fmac_f32_e32 v230, v147, v244
	v_mul_f32_e32 v230, v80, v230
	v_mul_f32_e32 v231, v231, v252
	v_fma_f32 v231, v231, v197, v213
	v_and_b32_e32 v244, 0xffff0000, v159
	v_fmac_f32_e32 v231, v147, v244
	v_mul_f32_e32 v231, v81, v231
	v_mul_f32_e32 v232, v232, v252
	v_fma_f32 v232, v232, v198, v214
	v_lshlrev_b32_e32 v244, 16, v160
	v_fmac_f32_e32 v232, v147, v244
	v_mul_f32_e32 v232, v74, v232
	v_mul_f32_e32 v233, v233, v252
	v_fma_f32 v233, v233, v199, v215
	v_and_b32_e32 v244, 0xffff0000, v160
	v_fmac_f32_e32 v233, v147, v244
	v_mul_f32_e32 v233, v75, v233
	v_mul_f32_e32 v234, v234, v252
	v_fma_f32 v234, v234, v200, v216
	v_lshlrev_b32_e32 v244, 16, v161
	v_fmac_f32_e32 v234, v147, v244
	v_mul_f32_e32 v234, v76, v234
	v_mul_f32_e32 v235, v235, v252
	v_fma_f32 v235, v235, v201, v217
	v_and_b32_e32 v244, 0xffff0000, v161
	v_fmac_f32_e32 v235, v147, v244
	v_mul_f32_e32 v235, v77, v235
	v_mul_f32_e32 v236, v236, v252
	v_fma_f32 v236, v236, v202, v218
	v_lshlrev_b32_e32 v244, 16, v162
	v_fmac_f32_e32 v236, v147, v244
	v_mul_f32_e32 v236, v70, v236
	v_mul_f32_e32 v237, v237, v252
	v_fma_f32 v237, v237, v203, v219
	v_and_b32_e32 v244, 0xffff0000, v162
	v_fmac_f32_e32 v237, v147, v244
	v_mul_f32_e32 v237, v71, v237
	v_mul_f32_e32 v238, v238, v252
	v_fma_f32 v238, v238, v204, v220
	v_lshlrev_b32_e32 v244, 16, v163
	v_fmac_f32_e32 v238, v147, v244
	v_mul_f32_e32 v238, v72, v238
	v_mul_f32_e32 v239, v239, v252
	v_fma_f32 v239, v239, v205, v221
	v_and_b32_e32 v244, 0xffff0000, v163
	v_fmac_f32_e32 v239, v147, v244
	v_mul_f32_e32 v239, v73, v239
	v_mul_f32_e32 v240, v240, v252
	v_fma_f32 v240, v240, v206, v222
	v_lshlrev_b32_e32 v244, 16, v164
	v_fmac_f32_e32 v240, v147, v244
	v_mul_f32_e32 v240, v66, v240
	v_mul_f32_e32 v241, v241, v252
	v_fma_f32 v241, v241, v207, v223
	v_and_b32_e32 v244, 0xffff0000, v164
	v_fmac_f32_e32 v241, v147, v244
	v_mul_f32_e32 v241, v67, v241
	v_mul_f32_e32 v242, v242, v252
	v_fma_f32 v242, v242, v208, v224
	v_lshlrev_b32_e32 v244, 16, v165
	v_fmac_f32_e32 v242, v147, v244
	v_mul_f32_e32 v242, v68, v242
	v_mul_f32_e32 v243, v243, v252
	v_fma_f32 v243, v243, v209, v225
	v_and_b32_e32 v244, 0xffff0000, v165
	v_fmac_f32_e32 v243, v147, v244
	v_mul_f32_e32 v243, v69, v243
	v_cvt_pk_bf16_f32 v228, v228, v229
	v_cvt_pk_bf16_f32 v229, v230, v231
	v_cvt_pk_bf16_f32 v230, v232, v233
	v_cvt_pk_bf16_f32 v231, v234, v235
	v_cvt_pk_bf16_f32 v232, v236, v237
	v_cvt_pk_bf16_f32 v233, v238, v239
	v_cvt_pk_bf16_f32 v234, v240, v241
	v_cvt_pk_bf16_f32 v235, v242, v243
	s_nop 1
	v_permlane16_swap_b32_e32 v228, v230
	v_permlane16_swap_b32_e32 v229, v231
	v_permlane16_swap_b32_e32 v232, v234
	v_permlane16_swap_b32_e32 v233, v235
	v_mov_b64_e32 v[248:249], v[226:227]
	s_add_i32 s0, s19, 80
	v_add_u32_e32 v253, s0, v0
	v_cmp_gt_i32_e32 vcc, s14, v253
	s_nop 1
	v_cndmask_b32_e32 v253, v168, v253, vcc
	v_mov_b64_e32 v[226:227], s[88:89]
	v_mad_i64_i32 v[226:227], s[0:1], v253, s15, v[226:227]
	v_mov_b32_e32 v244, v254
	v_mov_b32_e32 v245, 0
	v_lshl_add_u64 v[226:227], v[226:227], 0, v[244:245]
	global_load_dwordx4 v[150:153], v[226:227], off offset:0
	global_load_dwordx4 v[154:157], v[226:227], off offset:64
	v_ashrrev_i32_e32 v251, 31, v253
	v_mov_b32_e32 v250, v253
	v_lshlrev_b64 v[246:247], 11, v[250:251]
	v_lshl_add_u64 v[246:247], s[54:55], 0, v[246:247]
	v_lshl_add_u64 v[246:247], v[246:247], 0, v[244:245]
	global_load_dwordx4 v[158:161], v[246:247], off offset:0
	global_load_dwordx4 v[162:165], v[246:247], off offset:64
	v_lshlrev_b64 v[246:247], 6, v[250:251]
	v_lshl_add_u64 v[246:247], s[58:59], 0, v[246:247]
	v_lshl_add_u64 v[246:247], v[246:247], 0, s[20:21]
	global_load_dword v147, v[246:247], off
	s_add_i32 s0, s19, 48
	v_add_u32_e32 v253, s0, v0
	v_cmp_gt_i32_e32 vcc, s14, v253
	s_and_saveexec_b64 s[0:1], vcc
	global_store_dwordx4 v[248:249], v[228:231], off offset:0
	global_store_dwordx4 v[248:249], v[232:235], off offset:64
	s_or_b64 exec, exec, s[0:1]
	s_waitcnt vmcnt(5)
	v_permlane16_swap_b32_e32 v130, v132
	v_permlane16_swap_b32_e32 v131, v133
	v_permlane16_swap_b32_e32 v134, v136
	v_permlane16_swap_b32_e32 v135, v137
	v_permlane16_swap_b32_e32 v138, v140
	v_permlane16_swap_b32_e32 v139, v141
	v_permlane16_swap_b32_e32 v142, v144
	v_permlane16_swap_b32_e32 v143, v145
	v_lshlrev_b32_e32 v228, 16, v130
	v_and_b32_e32 v229, 0xffff0000, v130
	v_lshlrev_b32_e32 v230, 16, v131
	v_and_b32_e32 v231, 0xffff0000, v131
	v_lshlrev_b32_e32 v232, 16, v132
	v_and_b32_e32 v233, 0xffff0000, v132
	v_lshlrev_b32_e32 v234, 16, v133
	v_and_b32_e32 v235, 0xffff0000, v133
	v_lshlrev_b32_e32 v236, 16, v134
	v_and_b32_e32 v237, 0xffff0000, v134
	v_lshlrev_b32_e32 v238, 16, v135
	v_and_b32_e32 v239, 0xffff0000, v135
	v_lshlrev_b32_e32 v240, 16, v136
	v_and_b32_e32 v241, 0xffff0000, v136
	v_lshlrev_b32_e32 v242, 16, v137
	v_and_b32_e32 v243, 0xffff0000, v137
	v_add_f32_e32 v250, v228, v229
	v_add_f32_e32 v251, v230, v231
	v_add_f32_e32 v250, v250, v232
	v_add_f32_e32 v251, v251, v233
	v_add_f32_e32 v250, v250, v234
	v_add_f32_e32 v251, v251, v235
	v_add_f32_e32 v250, v250, v236
	v_add_f32_e32 v251, v251, v237
	v_add_f32_e32 v250, v250, v238
	v_add_f32_e32 v251, v251, v239
	v_add_f32_e32 v250, v250, v240
	v_add_f32_e32 v251, v251, v241
	v_add_f32_e32 v250, v250, v242
	v_add_f32_e32 v251, v251, v243
	v_add_f32_e32 v250, v250, v251
	ds_bpermute_b32 v251, v255, v250
	s_waitcnt lgkmcnt(0)
	v_add_f32_e32 v250, v250, v251
	ds_bpermute_b32 v251, v193, v250
	s_waitcnt lgkmcnt(0)
	v_add_f32_e32 v250, v250, v251
	v_fmac_f32_e32 v228, 0xbc800000, v250
	v_fmac_f32_e32 v229, 0xbc800000, v250
	v_fmac_f32_e32 v230, 0xbc800000, v250
	v_fmac_f32_e32 v231, 0xbc800000, v250
	v_fmac_f32_e32 v232, 0xbc800000, v250
	v_fmac_f32_e32 v233, 0xbc800000, v250
	v_fmac_f32_e32 v234, 0xbc800000, v250
	v_fmac_f32_e32 v235, 0xbc800000, v250
	v_fmac_f32_e32 v236, 0xbc800000, v250
	v_fmac_f32_e32 v237, 0xbc800000, v250
	v_fmac_f32_e32 v238, 0xbc800000, v250
	v_fmac_f32_e32 v239, 0xbc800000, v250
	v_fmac_f32_e32 v240, 0xbc800000, v250
	v_fmac_f32_e32 v241, 0xbc800000, v250
	v_fmac_f32_e32 v242, 0xbc800000, v250
	v_fmac_f32_e32 v243, 0xbc800000, v250
	v_mul_f32_e32 v250, v228, v228
	v_mul_f32_e32 v251, v229, v229
	v_fmac_f32_e32 v250, v230, v230
	v_fmac_f32_e32 v251, v231, v231
	v_fmac_f32_e32 v250, v232, v232
	v_fmac_f32_e32 v251, v233, v233
	v_fmac_f32_e32 v250, v234, v234
	v_fmac_f32_e32 v251, v235, v235
	v_fmac_f32_e32 v250, v236, v236
	v_fmac_f32_e32 v251, v237, v237
	v_fmac_f32_e32 v250, v238, v238
	v_fmac_f32_e32 v251, v239, v239
	v_fmac_f32_e32 v250, v240, v240
	v_fmac_f32_e32 v251, v241, v241
	v_fmac_f32_e32 v250, v242, v242
	v_fmac_f32_e32 v251, v243, v243
	v_add_f32_e32 v250, v250, v251
	ds_bpermute_b32 v251, v255, v250
	s_waitcnt lgkmcnt(0)
	v_add_f32_e32 v250, v250, v251
	ds_bpermute_b32 v251, v193, v250
	s_waitcnt lgkmcnt(0)
	v_add_f32_e32 v250, v250, v251
	v_fmamk_f32 v250, v250, 0x3c800000, v166
	v_mul_f32_e32 v251, 0x4b800000, v250
	v_cmp_gt_f32_e64 s[0:1], s16, v250
	s_nop 1
	v_cndmask_b32_e64 v250, v250, v251, s[0:1]
	v_rsq_f32_e32 v252, v250
	s_nop 0
	v_mul_f32_e32 v251, 0x45800000, v252
	v_cndmask_b32_e64 v252, v252, v251, s[0:1]
	v_mul_f32_e32 v228, v228, v252
	v_fma_f32 v228, v228, v194, v210
	v_lshlrev_b32_e32 v244, 16, v138
	v_fmac_f32_e32 v228, v146, v244
	v_mul_f32_e32 v228, v62, v228
	v_mul_f32_e32 v229, v229, v252
	v_fma_f32 v229, v229, v195, v211
	v_and_b32_e32 v244, 0xffff0000, v138
	v_fmac_f32_e32 v229, v146, v244
	v_mul_f32_e32 v229, v63, v229
	v_mul_f32_e32 v230, v230, v252
	v_fma_f32 v230, v230, v196, v212
	v_lshlrev_b32_e32 v244, 16, v139
	v_fmac_f32_e32 v230, v146, v244
	v_mul_f32_e32 v230, v64, v230
	v_mul_f32_e32 v231, v231, v252
	v_fma_f32 v231, v231, v197, v213
	v_and_b32_e32 v244, 0xffff0000, v139
	v_fmac_f32_e32 v231, v146, v244
	v_mul_f32_e32 v231, v65, v231
	v_mul_f32_e32 v232, v232, v252
	v_fma_f32 v232, v232, v198, v214
	v_lshlrev_b32_e32 v244, 16, v140
	v_fmac_f32_e32 v232, v146, v244
	v_mul_f32_e32 v232, v58, v232
	v_mul_f32_e32 v233, v233, v252
	v_fma_f32 v233, v233, v199, v215
	v_and_b32_e32 v244, 0xffff0000, v140
	v_fmac_f32_e32 v233, v146, v244
	v_mul_f32_e32 v233, v59, v233
	v_mul_f32_e32 v234, v234, v252
	v_fma_f32 v234, v234, v200, v216
	v_lshlrev_b32_e32 v244, 16, v141
	v_fmac_f32_e32 v234, v146, v244
	v_mul_f32_e32 v234, v60, v234
	v_mul_f32_e32 v235, v235, v252
	v_fma_f32 v235, v235, v201, v217
	v_and_b32_e32 v244, 0xffff0000, v141
	v_fmac_f32_e32 v235, v146, v244
	v_mul_f32_e32 v235, v61, v235
	v_mul_f32_e32 v236, v236, v252
	v_fma_f32 v236, v236, v202, v218
	v_lshlrev_b32_e32 v244, 16, v142
	v_fmac_f32_e32 v236, v146, v244
	v_mul_f32_e32 v236, v54, v236
	v_mul_f32_e32 v237, v237, v252
	v_fma_f32 v237, v237, v203, v219
	v_and_b32_e32 v244, 0xffff0000, v142
	v_fmac_f32_e32 v237, v146, v244
	v_mul_f32_e32 v237, v55, v237
	v_mul_f32_e32 v238, v238, v252
	v_fma_f32 v238, v238, v204, v220
	v_lshlrev_b32_e32 v244, 16, v143
	v_fmac_f32_e32 v238, v146, v244
	v_mul_f32_e32 v238, v56, v238
	v_mul_f32_e32 v239, v239, v252
	v_fma_f32 v239, v239, v205, v221
	v_and_b32_e32 v244, 0xffff0000, v143
	v_fmac_f32_e32 v239, v146, v244
	v_mul_f32_e32 v239, v57, v239
	v_mul_f32_e32 v240, v240, v252
	v_fma_f32 v240, v240, v206, v222
	v_lshlrev_b32_e32 v244, 16, v144
	v_fmac_f32_e32 v240, v146, v244
	v_mul_f32_e32 v240, v50, v240
	v_mul_f32_e32 v241, v241, v252
	v_fma_f32 v241, v241, v207, v223
	v_and_b32_e32 v244, 0xffff0000, v144
	v_fmac_f32_e32 v241, v146, v244
	v_mul_f32_e32 v241, v51, v241
	v_mul_f32_e32 v242, v242, v252
	v_fma_f32 v242, v242, v208, v224
	v_lshlrev_b32_e32 v244, 16, v145
	v_fmac_f32_e32 v242, v146, v244
	v_mul_f32_e32 v242, v52, v242
	v_mul_f32_e32 v243, v243, v252
	v_fma_f32 v243, v243, v209, v225
	v_and_b32_e32 v244, 0xffff0000, v145
	v_fmac_f32_e32 v243, v146, v244
	v_mul_f32_e32 v243, v53, v243
	v_cvt_pk_bf16_f32 v228, v228, v229
	v_cvt_pk_bf16_f32 v229, v230, v231
	v_cvt_pk_bf16_f32 v230, v232, v233
	v_cvt_pk_bf16_f32 v231, v234, v235
	v_cvt_pk_bf16_f32 v232, v236, v237
	v_cvt_pk_bf16_f32 v233, v238, v239
	v_cvt_pk_bf16_f32 v234, v240, v241
	v_cvt_pk_bf16_f32 v235, v242, v243
	s_nop 1
	v_permlane16_swap_b32_e32 v228, v230
	v_permlane16_swap_b32_e32 v229, v231
	v_permlane16_swap_b32_e32 v232, v234
	v_permlane16_swap_b32_e32 v233, v235
	v_mov_b64_e32 v[248:249], v[148:149]
	s_add_i32 s0, s19, 96
	v_add_u32_e32 v253, s0, v0
	v_cmp_gt_i32_e32 vcc, s14, v253
	s_nop 1
	v_cndmask_b32_e32 v253, v168, v253, vcc
	v_mov_b64_e32 v[148:149], s[88:89]
	v_mad_i64_i32 v[148:149], s[0:1], v253, s15, v[148:149]
	v_mov_b32_e32 v244, v254
	v_mov_b32_e32 v245, 0
	v_lshl_add_u64 v[148:149], v[148:149], 0, v[244:245]
	global_load_dwordx4 v[130:133], v[148:149], off offset:0
	global_load_dwordx4 v[134:137], v[148:149], off offset:64
	v_ashrrev_i32_e32 v251, 31, v253
	v_mov_b32_e32 v250, v253
	v_lshlrev_b64 v[246:247], 11, v[250:251]
	v_lshl_add_u64 v[246:247], s[54:55], 0, v[246:247]
	v_lshl_add_u64 v[246:247], v[246:247], 0, v[244:245]
	global_load_dwordx4 v[138:141], v[246:247], off offset:0
	global_load_dwordx4 v[142:145], v[246:247], off offset:64
	v_lshlrev_b64 v[246:247], 6, v[250:251]
	v_lshl_add_u64 v[246:247], s[58:59], 0, v[246:247]
	v_lshl_add_u64 v[246:247], v[246:247], 0, s[20:21]
	global_load_dword v146, v[246:247], off
	s_add_i32 s0, s19, 64
	v_add_u32_e32 v253, s0, v0
	v_cmp_gt_i32_e32 vcc, s14, v253
	s_and_saveexec_b64 s[0:1], vcc
	global_store_dwordx4 v[248:249], v[228:231], off offset:0
	global_store_dwordx4 v[248:249], v[232:235], off offset:64
	s_or_b64 exec, exec, s[0:1]
	s_waitcnt vmcnt(5)
	v_permlane16_swap_b32_e32 v150, v152
	v_permlane16_swap_b32_e32 v151, v153
	v_permlane16_swap_b32_e32 v154, v156
	v_permlane16_swap_b32_e32 v155, v157
	v_permlane16_swap_b32_e32 v158, v160
	v_permlane16_swap_b32_e32 v159, v161
	v_permlane16_swap_b32_e32 v162, v164
	v_permlane16_swap_b32_e32 v163, v165
	v_lshlrev_b32_e32 v228, 16, v150
	v_and_b32_e32 v229, 0xffff0000, v150
	v_lshlrev_b32_e32 v230, 16, v151
	v_and_b32_e32 v231, 0xffff0000, v151
	v_lshlrev_b32_e32 v232, 16, v152
	v_and_b32_e32 v233, 0xffff0000, v152
	v_lshlrev_b32_e32 v234, 16, v153
	v_and_b32_e32 v235, 0xffff0000, v153
	v_lshlrev_b32_e32 v236, 16, v154
	v_and_b32_e32 v237, 0xffff0000, v154
	v_lshlrev_b32_e32 v238, 16, v155
	v_and_b32_e32 v239, 0xffff0000, v155
	v_lshlrev_b32_e32 v240, 16, v156
	v_and_b32_e32 v241, 0xffff0000, v156
	v_lshlrev_b32_e32 v242, 16, v157
	v_and_b32_e32 v243, 0xffff0000, v157
	v_add_f32_e32 v250, v228, v229
	v_add_f32_e32 v251, v230, v231
	v_add_f32_e32 v250, v250, v232
	v_add_f32_e32 v251, v251, v233
	v_add_f32_e32 v250, v250, v234
	v_add_f32_e32 v251, v251, v235
	v_add_f32_e32 v250, v250, v236
	v_add_f32_e32 v251, v251, v237
	v_add_f32_e32 v250, v250, v238
	v_add_f32_e32 v251, v251, v239
	v_add_f32_e32 v250, v250, v240
	v_add_f32_e32 v251, v251, v241
	v_add_f32_e32 v250, v250, v242
	v_add_f32_e32 v251, v251, v243
	v_add_f32_e32 v250, v250, v251
	ds_bpermute_b32 v251, v255, v250
	s_waitcnt lgkmcnt(0)
	v_add_f32_e32 v250, v250, v251
	ds_bpermute_b32 v251, v193, v250
	s_waitcnt lgkmcnt(0)
	v_add_f32_e32 v250, v250, v251
	v_fmac_f32_e32 v228, 0xbc800000, v250
	v_fmac_f32_e32 v229, 0xbc800000, v250
	v_fmac_f32_e32 v230, 0xbc800000, v250
	v_fmac_f32_e32 v231, 0xbc800000, v250
	v_fmac_f32_e32 v232, 0xbc800000, v250
	v_fmac_f32_e32 v233, 0xbc800000, v250
	v_fmac_f32_e32 v234, 0xbc800000, v250
	v_fmac_f32_e32 v235, 0xbc800000, v250
	v_fmac_f32_e32 v236, 0xbc800000, v250
	v_fmac_f32_e32 v237, 0xbc800000, v250
	v_fmac_f32_e32 v238, 0xbc800000, v250
	v_fmac_f32_e32 v239, 0xbc800000, v250
	v_fmac_f32_e32 v240, 0xbc800000, v250
	v_fmac_f32_e32 v241, 0xbc800000, v250
	v_fmac_f32_e32 v242, 0xbc800000, v250
	v_fmac_f32_e32 v243, 0xbc800000, v250
	v_mul_f32_e32 v250, v228, v228
	v_mul_f32_e32 v251, v229, v229
	v_fmac_f32_e32 v250, v230, v230
	v_fmac_f32_e32 v251, v231, v231
	v_fmac_f32_e32 v250, v232, v232
	v_fmac_f32_e32 v251, v233, v233
	v_fmac_f32_e32 v250, v234, v234
	v_fmac_f32_e32 v251, v235, v235
	v_fmac_f32_e32 v250, v236, v236
	v_fmac_f32_e32 v251, v237, v237
	v_fmac_f32_e32 v250, v238, v238
	v_fmac_f32_e32 v251, v239, v239
	v_fmac_f32_e32 v250, v240, v240
	v_fmac_f32_e32 v251, v241, v241
	v_fmac_f32_e32 v250, v242, v242
	v_fmac_f32_e32 v251, v243, v243
	v_add_f32_e32 v250, v250, v251
	ds_bpermute_b32 v251, v255, v250
	s_waitcnt lgkmcnt(0)
	v_add_f32_e32 v250, v250, v251
	ds_bpermute_b32 v251, v193, v250
	s_waitcnt lgkmcnt(0)
	v_add_f32_e32 v250, v250, v251
	v_fmamk_f32 v250, v250, 0x3c800000, v166
	v_mul_f32_e32 v251, 0x4b800000, v250
	v_cmp_gt_f32_e64 s[0:1], s16, v250
	s_nop 1
	v_cndmask_b32_e64 v250, v250, v251, s[0:1]
	v_rsq_f32_e32 v252, v250
	s_nop 0
	v_mul_f32_e32 v251, 0x45800000, v252
	v_cndmask_b32_e64 v252, v252, v251, s[0:1]
	v_mul_f32_e32 v228, v228, v252
	v_fma_f32 v228, v228, v194, v210
	v_lshlrev_b32_e32 v244, 16, v158
	v_fmac_f32_e32 v228, v147, v244
	v_mul_f32_e32 v228, v46, v228
	v_mul_f32_e32 v229, v229, v252
	v_fma_f32 v229, v229, v195, v211
	v_and_b32_e32 v244, 0xffff0000, v158
	v_fmac_f32_e32 v229, v147, v244
	v_mul_f32_e32 v229, v47, v229
	v_mul_f32_e32 v230, v230, v252
	v_fma_f32 v230, v230, v196, v212
	v_lshlrev_b32_e32 v244, 16, v159
	v_fmac_f32_e32 v230, v147, v244
	v_mul_f32_e32 v230, v48, v230
	v_mul_f32_e32 v231, v231, v252
	v_fma_f32 v231, v231, v197, v213
	v_and_b32_e32 v244, 0xffff0000, v159
	v_fmac_f32_e32 v231, v147, v244
	v_mul_f32_e32 v231, v49, v231
	v_mul_f32_e32 v232, v232, v252
	v_fma_f32 v232, v232, v198, v214
	v_lshlrev_b32_e32 v244, 16, v160
	v_fmac_f32_e32 v232, v147, v244
	v_mul_f32_e32 v232, v42, v232
	v_mul_f32_e32 v233, v233, v252
	v_fma_f32 v233, v233, v199, v215
	v_and_b32_e32 v244, 0xffff0000, v160
	v_fmac_f32_e32 v233, v147, v244
	v_mul_f32_e32 v233, v43, v233
	v_mul_f32_e32 v234, v234, v252
	v_fma_f32 v234, v234, v200, v216
	v_lshlrev_b32_e32 v244, 16, v161
	v_fmac_f32_e32 v234, v147, v244
	v_mul_f32_e32 v234, v44, v234
	v_mul_f32_e32 v235, v235, v252
	v_fma_f32 v235, v235, v201, v217
	v_and_b32_e32 v244, 0xffff0000, v161
	v_fmac_f32_e32 v235, v147, v244
	v_mul_f32_e32 v235, v45, v235
	v_mul_f32_e32 v236, v236, v252
	v_fma_f32 v236, v236, v202, v218
	v_lshlrev_b32_e32 v244, 16, v162
	v_fmac_f32_e32 v236, v147, v244
	v_mul_f32_e32 v236, v38, v236
	v_mul_f32_e32 v237, v237, v252
	v_fma_f32 v237, v237, v203, v219
	v_and_b32_e32 v244, 0xffff0000, v162
	v_fmac_f32_e32 v237, v147, v244
	v_mul_f32_e32 v237, v39, v237
	v_mul_f32_e32 v238, v238, v252
	v_fma_f32 v238, v238, v204, v220
	v_lshlrev_b32_e32 v244, 16, v163
	v_fmac_f32_e32 v238, v147, v244
	v_mul_f32_e32 v238, v40, v238
	v_mul_f32_e32 v239, v239, v252
	v_fma_f32 v239, v239, v205, v221
	v_and_b32_e32 v244, 0xffff0000, v163
	v_fmac_f32_e32 v239, v147, v244
	v_mul_f32_e32 v239, v41, v239
	v_mul_f32_e32 v240, v240, v252
	v_fma_f32 v240, v240, v206, v222
	v_lshlrev_b32_e32 v244, 16, v164
	v_fmac_f32_e32 v240, v147, v244
	v_mul_f32_e32 v240, v34, v240
	v_mul_f32_e32 v241, v241, v252
	v_fma_f32 v241, v241, v207, v223
	v_and_b32_e32 v244, 0xffff0000, v164
	v_fmac_f32_e32 v241, v147, v244
	v_mul_f32_e32 v241, v35, v241
	v_mul_f32_e32 v242, v242, v252
	v_fma_f32 v242, v242, v208, v224
	v_lshlrev_b32_e32 v244, 16, v165
	v_fmac_f32_e32 v242, v147, v244
	v_mul_f32_e32 v242, v36, v242
	v_mul_f32_e32 v243, v243, v252
	v_fma_f32 v243, v243, v209, v225
	v_and_b32_e32 v244, 0xffff0000, v165
	v_fmac_f32_e32 v243, v147, v244
	v_mul_f32_e32 v243, v37, v243
	v_cvt_pk_bf16_f32 v228, v228, v229
	v_cvt_pk_bf16_f32 v229, v230, v231
	v_cvt_pk_bf16_f32 v230, v232, v233
	v_cvt_pk_bf16_f32 v231, v234, v235
	v_cvt_pk_bf16_f32 v232, v236, v237
	v_cvt_pk_bf16_f32 v233, v238, v239
	v_cvt_pk_bf16_f32 v234, v240, v241
	v_cvt_pk_bf16_f32 v235, v242, v243
	s_nop 1
	v_permlane16_swap_b32_e32 v228, v230
	v_permlane16_swap_b32_e32 v229, v231
	v_permlane16_swap_b32_e32 v232, v234
	v_permlane16_swap_b32_e32 v233, v235
	v_mov_b64_e32 v[248:249], v[226:227]
	s_add_i32 s0, s19, 112
	v_add_u32_e32 v253, s0, v0
	v_cmp_gt_i32_e32 vcc, s14, v253
	s_nop 1
	v_cndmask_b32_e32 v253, v168, v253, vcc
	v_mov_b64_e32 v[226:227], s[88:89]
	v_mad_i64_i32 v[226:227], s[0:1], v253, s15, v[226:227]
	v_mov_b32_e32 v244, v254
	v_mov_b32_e32 v245, 0
	v_lshl_add_u64 v[226:227], v[226:227], 0, v[244:245]
	global_load_dwordx4 v[150:153], v[226:227], off offset:0
	global_load_dwordx4 v[154:157], v[226:227], off offset:64
	v_ashrrev_i32_e32 v251, 31, v253
	v_mov_b32_e32 v250, v253
	v_lshlrev_b64 v[246:247], 11, v[250:251]
	v_lshl_add_u64 v[246:247], s[54:55], 0, v[246:247]
	v_lshl_add_u64 v[246:247], v[246:247], 0, v[244:245]
	global_load_dwordx4 v[158:161], v[246:247], off offset:0
	global_load_dwordx4 v[162:165], v[246:247], off offset:64
	v_lshlrev_b64 v[246:247], 6, v[250:251]
	v_lshl_add_u64 v[246:247], s[58:59], 0, v[246:247]
	v_lshl_add_u64 v[246:247], v[246:247], 0, s[20:21]
	global_load_dword v147, v[246:247], off
	s_add_i32 s0, s19, 80
	v_add_u32_e32 v253, s0, v0
	v_cmp_gt_i32_e32 vcc, s14, v253
	s_and_saveexec_b64 s[0:1], vcc
	global_store_dwordx4 v[248:249], v[228:231], off offset:0
	global_store_dwordx4 v[248:249], v[232:235], off offset:64
	s_or_b64 exec, exec, s[0:1]
	s_waitcnt vmcnt(5)
	v_permlane16_swap_b32_e32 v130, v132
	v_permlane16_swap_b32_e32 v131, v133
	v_permlane16_swap_b32_e32 v134, v136
	v_permlane16_swap_b32_e32 v135, v137
	v_permlane16_swap_b32_e32 v138, v140
	v_permlane16_swap_b32_e32 v139, v141
	v_permlane16_swap_b32_e32 v142, v144
	v_permlane16_swap_b32_e32 v143, v145
	v_lshlrev_b32_e32 v228, 16, v130
	v_and_b32_e32 v229, 0xffff0000, v130
	v_lshlrev_b32_e32 v230, 16, v131
	v_and_b32_e32 v231, 0xffff0000, v131
	v_lshlrev_b32_e32 v232, 16, v132
	v_and_b32_e32 v233, 0xffff0000, v132
	v_lshlrev_b32_e32 v234, 16, v133
	v_and_b32_e32 v235, 0xffff0000, v133
	v_lshlrev_b32_e32 v236, 16, v134
	v_and_b32_e32 v237, 0xffff0000, v134
	v_lshlrev_b32_e32 v238, 16, v135
	v_and_b32_e32 v239, 0xffff0000, v135
	v_lshlrev_b32_e32 v240, 16, v136
	v_and_b32_e32 v241, 0xffff0000, v136
	v_lshlrev_b32_e32 v242, 16, v137
	v_and_b32_e32 v243, 0xffff0000, v137
	v_add_f32_e32 v250, v228, v229
	v_add_f32_e32 v251, v230, v231
	v_add_f32_e32 v250, v250, v232
	v_add_f32_e32 v251, v251, v233
	v_add_f32_e32 v250, v250, v234
	v_add_f32_e32 v251, v251, v235
	v_add_f32_e32 v250, v250, v236
	v_add_f32_e32 v251, v251, v237
	v_add_f32_e32 v250, v250, v238
	v_add_f32_e32 v251, v251, v239
	v_add_f32_e32 v250, v250, v240
	v_add_f32_e32 v251, v251, v241
	v_add_f32_e32 v250, v250, v242
	v_add_f32_e32 v251, v251, v243
	v_add_f32_e32 v250, v250, v251
	ds_bpermute_b32 v251, v255, v250
	s_waitcnt lgkmcnt(0)
	v_add_f32_e32 v250, v250, v251
	ds_bpermute_b32 v251, v193, v250
	s_waitcnt lgkmcnt(0)
	v_add_f32_e32 v250, v250, v251
	v_fmac_f32_e32 v228, 0xbc800000, v250
	v_fmac_f32_e32 v229, 0xbc800000, v250
	v_fmac_f32_e32 v230, 0xbc800000, v250
	v_fmac_f32_e32 v231, 0xbc800000, v250
	v_fmac_f32_e32 v232, 0xbc800000, v250
	v_fmac_f32_e32 v233, 0xbc800000, v250
	v_fmac_f32_e32 v234, 0xbc800000, v250
	v_fmac_f32_e32 v235, 0xbc800000, v250
	v_fmac_f32_e32 v236, 0xbc800000, v250
	v_fmac_f32_e32 v237, 0xbc800000, v250
	v_fmac_f32_e32 v238, 0xbc800000, v250
	v_fmac_f32_e32 v239, 0xbc800000, v250
	v_fmac_f32_e32 v240, 0xbc800000, v250
	v_fmac_f32_e32 v241, 0xbc800000, v250
	v_fmac_f32_e32 v242, 0xbc800000, v250
	v_fmac_f32_e32 v243, 0xbc800000, v250
	v_mul_f32_e32 v250, v228, v228
	v_mul_f32_e32 v251, v229, v229
	v_fmac_f32_e32 v250, v230, v230
	v_fmac_f32_e32 v251, v231, v231
	v_fmac_f32_e32 v250, v232, v232
	v_fmac_f32_e32 v251, v233, v233
	v_fmac_f32_e32 v250, v234, v234
	v_fmac_f32_e32 v251, v235, v235
	v_fmac_f32_e32 v250, v236, v236
	v_fmac_f32_e32 v251, v237, v237
	v_fmac_f32_e32 v250, v238, v238
	v_fmac_f32_e32 v251, v239, v239
	v_fmac_f32_e32 v250, v240, v240
	v_fmac_f32_e32 v251, v241, v241
	v_fmac_f32_e32 v250, v242, v242
	v_fmac_f32_e32 v251, v243, v243
	v_add_f32_e32 v250, v250, v251
	ds_bpermute_b32 v251, v255, v250
	s_waitcnt lgkmcnt(0)
	v_add_f32_e32 v250, v250, v251
	ds_bpermute_b32 v251, v193, v250
	s_waitcnt lgkmcnt(0)
	v_add_f32_e32 v250, v250, v251
	v_fmamk_f32 v250, v250, 0x3c800000, v166
	v_mul_f32_e32 v251, 0x4b800000, v250
	v_cmp_gt_f32_e64 s[0:1], s16, v250
	s_nop 1
	v_cndmask_b32_e64 v250, v250, v251, s[0:1]
	v_rsq_f32_e32 v252, v250
	s_nop 0
	v_mul_f32_e32 v251, 0x45800000, v252
	v_cndmask_b32_e64 v252, v252, v251, s[0:1]
	v_mul_f32_e32 v228, v228, v252
	v_fma_f32 v228, v228, v194, v210
	v_lshlrev_b32_e32 v244, 16, v138
	v_fmac_f32_e32 v228, v146, v244
	v_mul_f32_e32 v228, v30, v228
	v_mul_f32_e32 v229, v229, v252
	v_fma_f32 v229, v229, v195, v211
	v_and_b32_e32 v244, 0xffff0000, v138
	v_fmac_f32_e32 v229, v146, v244
	v_mul_f32_e32 v229, v31, v229
	v_mul_f32_e32 v230, v230, v252
	v_fma_f32 v230, v230, v196, v212
	v_lshlrev_b32_e32 v244, 16, v139
	v_fmac_f32_e32 v230, v146, v244
	v_mul_f32_e32 v230, v32, v230
	v_mul_f32_e32 v231, v231, v252
	v_fma_f32 v231, v231, v197, v213
	v_and_b32_e32 v244, 0xffff0000, v139
	v_fmac_f32_e32 v231, v146, v244
	v_mul_f32_e32 v231, v33, v231
	v_mul_f32_e32 v232, v232, v252
	v_fma_f32 v232, v232, v198, v214
	v_lshlrev_b32_e32 v244, 16, v140
	v_fmac_f32_e32 v232, v146, v244
	v_mul_f32_e32 v232, v26, v232
	v_mul_f32_e32 v233, v233, v252
	v_fma_f32 v233, v233, v199, v215
	v_and_b32_e32 v244, 0xffff0000, v140
	v_fmac_f32_e32 v233, v146, v244
	v_mul_f32_e32 v233, v27, v233
	v_mul_f32_e32 v234, v234, v252
	v_fma_f32 v234, v234, v200, v216
	v_lshlrev_b32_e32 v244, 16, v141
	v_fmac_f32_e32 v234, v146, v244
	v_mul_f32_e32 v234, v28, v234
	v_mul_f32_e32 v235, v235, v252
	v_fma_f32 v235, v235, v201, v217
	v_and_b32_e32 v244, 0xffff0000, v141
	v_fmac_f32_e32 v235, v146, v244
	v_mul_f32_e32 v235, v29, v235
	v_mul_f32_e32 v236, v236, v252
	v_fma_f32 v236, v236, v202, v218
	v_lshlrev_b32_e32 v244, 16, v142
	v_fmac_f32_e32 v236, v146, v244
	v_mul_f32_e32 v236, v22, v236
	v_mul_f32_e32 v237, v237, v252
	v_fma_f32 v237, v237, v203, v219
	v_and_b32_e32 v244, 0xffff0000, v142
	v_fmac_f32_e32 v237, v146, v244
	v_mul_f32_e32 v237, v23, v237
	v_mul_f32_e32 v238, v238, v252
	v_fma_f32 v238, v238, v204, v220
	v_lshlrev_b32_e32 v244, 16, v143
	v_fmac_f32_e32 v238, v146, v244
	v_mul_f32_e32 v238, v24, v238
	v_mul_f32_e32 v239, v239, v252
	v_fma_f32 v239, v239, v205, v221
	v_and_b32_e32 v244, 0xffff0000, v143
	v_fmac_f32_e32 v239, v146, v244
	v_mul_f32_e32 v239, v25, v239
	v_mul_f32_e32 v240, v240, v252
	v_fma_f32 v240, v240, v206, v222
	v_lshlrev_b32_e32 v244, 16, v144
	v_fmac_f32_e32 v240, v146, v244
	v_mul_f32_e32 v240, v18, v240
	v_mul_f32_e32 v241, v241, v252
	v_fma_f32 v241, v241, v207, v223
	v_and_b32_e32 v244, 0xffff0000, v144
	v_fmac_f32_e32 v241, v146, v244
	v_mul_f32_e32 v241, v19, v241
	v_mul_f32_e32 v242, v242, v252
	v_fma_f32 v242, v242, v208, v224
	v_lshlrev_b32_e32 v244, 16, v145
	v_fmac_f32_e32 v242, v146, v244
	v_mul_f32_e32 v242, v20, v242
	v_mul_f32_e32 v243, v243, v252
	v_fma_f32 v243, v243, v209, v225
	v_and_b32_e32 v244, 0xffff0000, v145
	v_fmac_f32_e32 v243, v146, v244
	v_mul_f32_e32 v243, v21, v243
	v_cvt_pk_bf16_f32 v228, v228, v229
	v_cvt_pk_bf16_f32 v229, v230, v231
	v_cvt_pk_bf16_f32 v230, v232, v233
	v_cvt_pk_bf16_f32 v231, v234, v235
	v_cvt_pk_bf16_f32 v232, v236, v237
	v_cvt_pk_bf16_f32 v233, v238, v239
	v_cvt_pk_bf16_f32 v234, v240, v241
	v_cvt_pk_bf16_f32 v235, v242, v243
	s_nop 1
	v_permlane16_swap_b32_e32 v228, v230
	v_permlane16_swap_b32_e32 v229, v231
	v_permlane16_swap_b32_e32 v232, v234
	v_permlane16_swap_b32_e32 v233, v235
	s_add_i32 s0, s19, 96
	v_add_u32_e32 v253, s0, v0
	v_cmp_gt_i32_e32 vcc, s14, v253
	s_and_saveexec_b64 s[0:1], vcc
	global_store_dwordx4 v[148:149], v[228:231], off offset:0
	global_store_dwordx4 v[148:149], v[232:235], off offset:64
	s_or_b64 exec, exec, s[0:1]
	s_waitcnt vmcnt(0)
	v_permlane16_swap_b32_e32 v150, v152
	v_permlane16_swap_b32_e32 v151, v153
	v_permlane16_swap_b32_e32 v154, v156
	v_permlane16_swap_b32_e32 v155, v157
	v_permlane16_swap_b32_e32 v158, v160
	v_permlane16_swap_b32_e32 v159, v161
	v_permlane16_swap_b32_e32 v162, v164
	v_permlane16_swap_b32_e32 v163, v165
	v_lshlrev_b32_e32 v228, 16, v150
	v_and_b32_e32 v229, 0xffff0000, v150
	v_lshlrev_b32_e32 v230, 16, v151
	v_and_b32_e32 v231, 0xffff0000, v151
	v_lshlrev_b32_e32 v232, 16, v152
	v_and_b32_e32 v233, 0xffff0000, v152
	v_lshlrev_b32_e32 v234, 16, v153
	v_and_b32_e32 v235, 0xffff0000, v153
	v_lshlrev_b32_e32 v236, 16, v154
	v_and_b32_e32 v237, 0xffff0000, v154
	v_lshlrev_b32_e32 v238, 16, v155
	v_and_b32_e32 v239, 0xffff0000, v155
	v_lshlrev_b32_e32 v240, 16, v156
	v_and_b32_e32 v241, 0xffff0000, v156
	v_lshlrev_b32_e32 v242, 16, v157
	v_and_b32_e32 v243, 0xffff0000, v157
	v_add_f32_e32 v250, v228, v229
	v_add_f32_e32 v251, v230, v231
	v_add_f32_e32 v250, v250, v232
	v_add_f32_e32 v251, v251, v233
	v_add_f32_e32 v250, v250, v234
	v_add_f32_e32 v251, v251, v235
	v_add_f32_e32 v250, v250, v236
	v_add_f32_e32 v251, v251, v237
	v_add_f32_e32 v250, v250, v238
	v_add_f32_e32 v251, v251, v239
	v_add_f32_e32 v250, v250, v240
	v_add_f32_e32 v251, v251, v241
	v_add_f32_e32 v250, v250, v242
	v_add_f32_e32 v251, v251, v243
	v_add_f32_e32 v250, v250, v251
	ds_bpermute_b32 v251, v255, v250
	s_waitcnt lgkmcnt(0)
	v_add_f32_e32 v250, v250, v251
	ds_bpermute_b32 v251, v193, v250
	s_waitcnt lgkmcnt(0)
	v_add_f32_e32 v250, v250, v251
	v_fmac_f32_e32 v228, 0xbc800000, v250
	v_fmac_f32_e32 v229, 0xbc800000, v250
	v_fmac_f32_e32 v230, 0xbc800000, v250
	v_fmac_f32_e32 v231, 0xbc800000, v250
	v_fmac_f32_e32 v232, 0xbc800000, v250
	v_fmac_f32_e32 v233, 0xbc800000, v250
	v_fmac_f32_e32 v234, 0xbc800000, v250
	v_fmac_f32_e32 v235, 0xbc800000, v250
	v_fmac_f32_e32 v236, 0xbc800000, v250
	v_fmac_f32_e32 v237, 0xbc800000, v250
	v_fmac_f32_e32 v238, 0xbc800000, v250
	v_fmac_f32_e32 v239, 0xbc800000, v250
	v_fmac_f32_e32 v240, 0xbc800000, v250
	v_fmac_f32_e32 v241, 0xbc800000, v250
	v_fmac_f32_e32 v242, 0xbc800000, v250
	v_fmac_f32_e32 v243, 0xbc800000, v250
	v_mul_f32_e32 v250, v228, v228
	v_mul_f32_e32 v251, v229, v229
	v_fmac_f32_e32 v250, v230, v230
	v_fmac_f32_e32 v251, v231, v231
	v_fmac_f32_e32 v250, v232, v232
	v_fmac_f32_e32 v251, v233, v233
	v_fmac_f32_e32 v250, v234, v234
	v_fmac_f32_e32 v251, v235, v235
	v_fmac_f32_e32 v250, v236, v236
	v_fmac_f32_e32 v251, v237, v237
	v_fmac_f32_e32 v250, v238, v238
	v_fmac_f32_e32 v251, v239, v239
	v_fmac_f32_e32 v250, v240, v240
	v_fmac_f32_e32 v251, v241, v241
	v_fmac_f32_e32 v250, v242, v242
	v_fmac_f32_e32 v251, v243, v243
	v_add_f32_e32 v250, v250, v251
	ds_bpermute_b32 v251, v255, v250
	s_waitcnt lgkmcnt(0)
	v_add_f32_e32 v250, v250, v251
	ds_bpermute_b32 v251, v193, v250
	s_waitcnt lgkmcnt(0)
	v_add_f32_e32 v250, v250, v251
	v_fmamk_f32 v250, v250, 0x3c800000, v166
	v_mul_f32_e32 v251, 0x4b800000, v250
	v_cmp_gt_f32_e64 s[0:1], s16, v250
	s_nop 1
	v_cndmask_b32_e64 v250, v250, v251, s[0:1]
	v_rsq_f32_e32 v252, v250
	s_nop 0
	v_mul_f32_e32 v251, 0x45800000, v252
	v_cndmask_b32_e64 v252, v252, v251, s[0:1]
	v_mul_f32_e32 v228, v228, v252
	v_fma_f32 v228, v228, v194, v210
	v_lshlrev_b32_e32 v244, 16, v158
	v_fmac_f32_e32 v228, v147, v244
	v_mul_f32_e32 v228, v14, v228
	v_mul_f32_e32 v229, v229, v252
	v_fma_f32 v229, v229, v195, v211
	v_and_b32_e32 v244, 0xffff0000, v158
	v_fmac_f32_e32 v229, v147, v244
	v_mul_f32_e32 v229, v15, v229
	v_mul_f32_e32 v230, v230, v252
	v_fma_f32 v230, v230, v196, v212
	v_lshlrev_b32_e32 v244, 16, v159
	v_fmac_f32_e32 v230, v147, v244
	v_mul_f32_e32 v230, v16, v230
	v_mul_f32_e32 v231, v231, v252
	v_fma_f32 v231, v231, v197, v213
	v_and_b32_e32 v244, 0xffff0000, v159
	v_fmac_f32_e32 v231, v147, v244
	v_mul_f32_e32 v231, v17, v231
	v_mul_f32_e32 v232, v232, v252
	v_fma_f32 v232, v232, v198, v214
	v_lshlrev_b32_e32 v244, 16, v160
	v_fmac_f32_e32 v232, v147, v244
	v_mul_f32_e32 v232, v10, v232
	v_mul_f32_e32 v233, v233, v252
	v_fma_f32 v233, v233, v199, v215
	v_and_b32_e32 v244, 0xffff0000, v160
	v_fmac_f32_e32 v233, v147, v244
	v_mul_f32_e32 v233, v11, v233
	v_mul_f32_e32 v234, v234, v252
	v_fma_f32 v234, v234, v200, v216
	v_lshlrev_b32_e32 v244, 16, v161
	v_fmac_f32_e32 v234, v147, v244
	v_mul_f32_e32 v234, v12, v234
	v_mul_f32_e32 v235, v235, v252
	v_fma_f32 v235, v235, v201, v217
	v_and_b32_e32 v244, 0xffff0000, v161
	v_fmac_f32_e32 v235, v147, v244
	v_mul_f32_e32 v235, v13, v235
	v_mul_f32_e32 v236, v236, v252
	v_fma_f32 v236, v236, v202, v218
	v_lshlrev_b32_e32 v244, 16, v162
	v_fmac_f32_e32 v236, v147, v244
	v_mul_f32_e32 v236, v6, v236
	v_mul_f32_e32 v237, v237, v252
	v_fma_f32 v237, v237, v203, v219
	v_and_b32_e32 v244, 0xffff0000, v162
	v_fmac_f32_e32 v237, v147, v244
	v_mul_f32_e32 v237, v7, v237
	v_mul_f32_e32 v238, v238, v252
	v_fma_f32 v238, v238, v204, v220
	v_lshlrev_b32_e32 v244, 16, v163
	v_fmac_f32_e32 v238, v147, v244
	v_mul_f32_e32 v238, v8, v238
	v_mul_f32_e32 v239, v239, v252
	v_fma_f32 v239, v239, v205, v221
	v_and_b32_e32 v244, 0xffff0000, v163
	v_fmac_f32_e32 v239, v147, v244
	v_mul_f32_e32 v239, v9, v239
	v_mul_f32_e32 v240, v240, v252
	v_fma_f32 v240, v240, v206, v222
	v_lshlrev_b32_e32 v244, 16, v164
	v_fmac_f32_e32 v240, v147, v244
	v_mul_f32_e32 v240, v2, v240
	v_mul_f32_e32 v241, v241, v252
	v_fma_f32 v241, v241, v207, v223
	v_and_b32_e32 v244, 0xffff0000, v164
	v_fmac_f32_e32 v241, v147, v244
	v_mul_f32_e32 v241, v3, v241
	v_mul_f32_e32 v242, v242, v252
	v_fma_f32 v242, v242, v208, v224
	v_lshlrev_b32_e32 v244, 16, v165
	v_fmac_f32_e32 v242, v147, v244
	v_mul_f32_e32 v242, v4, v242
	v_mul_f32_e32 v243, v243, v252
	v_fma_f32 v243, v243, v209, v225
	v_and_b32_e32 v244, 0xffff0000, v165
	v_fmac_f32_e32 v243, v147, v244
	v_mul_f32_e32 v243, v5, v243
	v_cvt_pk_bf16_f32 v228, v228, v229
	v_cvt_pk_bf16_f32 v229, v230, v231
	v_cvt_pk_bf16_f32 v230, v232, v233
	v_cvt_pk_bf16_f32 v231, v234, v235
	v_cvt_pk_bf16_f32 v232, v236, v237
	v_cvt_pk_bf16_f32 v233, v238, v239
	v_cvt_pk_bf16_f32 v234, v240, v241
	v_cvt_pk_bf16_f32 v235, v242, v243
	s_nop 1
	v_permlane16_swap_b32_e32 v228, v230
	v_permlane16_swap_b32_e32 v229, v231
	v_permlane16_swap_b32_e32 v232, v234
	v_permlane16_swap_b32_e32 v233, v235
	s_add_i32 s0, s19, 112
	v_add_u32_e32 v253, s0, v0
	v_cmp_gt_i32_e32 vcc, s14, v253
	s_and_saveexec_b64 s[0:1], vcc
	global_store_dwordx4 v[226:227], v[228:231], off offset:0
	global_store_dwordx4 v[226:227], v[232:235], off offset:64
	s_or_b64 exec, exec, s[0:1]
	s_mov_b64 s[0:1], exec
	s_branch .LBB0_1246
